# selected-key attention (layer 1) prompt-unit epilogue: gate loads hoisted, 16-byte loads and stores via v_permlane32_swap pairs, on top of the widened layer 0/3 epilogues
# speedup vs baseline: 1.0050x; 1.0050x over previous
; #define GAS __attribute__((address_space(1)))
; __device__ __forceinline__ unsigned cvtpk(float lo, float hi) { typedef __bf16 b2 __attribute__((ext_vector_type(2))); f32x2 v = {lo, hi}; b2 b = __builtin_convertvector(v, b2); return __builtin_bit_cast(unsigned, b); }
;     ...
;         const bf16* GB = (const bf16*)(F.ws + WS_GB) + (size_t)qrow * D + hcol; bf16* orow = OB + (size_t)qrow * D + hcol;
; #pragma unroll
;         for (int d = 0; d < 4; ++d)
; #pragma unroll
;             for (int rg = 0; rg < 4; ++rg) { const int dc = d * 32 + 8 * rg + 4 * hi; const v2u gg = *(const GAS v2u*)(GB + dc);
;                 const float y0 = o[d][4 * rg + 0] * inv * bf_lo(gg.x), y1 = o[d][4 * rg + 1] * inv * bf_hi(gg.x), y2 = o[d][4 * rg + 2] * inv * bf_lo(gg.y), y3 = o[d][4 * rg + 3] * inv * bf_hi(gg.y);
;                 v2u wv; wv.x = cvtpk(y0, y1); wv.y = cvtpk(y2, y3); *(GAS v2u*)(orow + dc) = wv; }
.LBB0_2094:
	v_mbcnt_hi_u32_b32 v2, -1, v165
	v_and_b32_e32 v7, 64, v2
	v_lshlrev_b64 v[4:5], 11, v[142:143]
	v_xor_b32_e32 v6, 32, v2
	v_add_u32_e32 v7, 64, v7
	v_readlane_b32 s4, v255, 29
	v_cmp_lt_i32_e32 vcc, v6, v7
	v_lshlrev_b64 v[4:5], 1, v[4:5]
	v_readlane_b32 s5, v255, 30
	v_cndmask_b32_e32 v2, v2, v6, vcc
	s_mov_b32 s71, s1
	v_lshl_add_u64 v[6:7], s[4:5], 0, v[4:5]
	v_mov_b32_e32 v83, v3
	v_lshl_add_u64 v[6:7], v[6:7], 0, s[70:71]
	v_lshlrev_b64 v[8:9], 1, v[82:83]
	s_waitcnt lgkmcnt(0)
	s_barrier
	v_lshl_add_u64 v[6:7], v[6:7], 0, v[8:9]
	v_mbcnt_hi_u32_b32 v124, -1, v165
	v_mov_b32_e32 v125, 0
	v_lshrrev_b32_e32 v124, 5, v124
	v_lshlrev_b32_e32 v124, 3, v124
	v_lshl_add_u64 v[4:5], s[86:87], 0, v[4:5]
	v_lshl_add_u64 v[6:7], v[6:7], 0, v[124:125]
	v_lshl_add_u64 v[4:5], v[4:5], 0, s[70:71]
	global_load_dwordx4 v[84:87], v[6:7], off
	global_load_dwordx4 v[88:91], v[6:7], off offset:32
	global_load_dwordx4 v[92:95], v[6:7], off offset:64
	global_load_dwordx4 v[96:99], v[6:7], off offset:96
	global_load_dwordx4 v[100:103], v[6:7], off offset:128
	global_load_dwordx4 v[104:107], v[6:7], off offset:160
	global_load_dwordx4 v[108:111], v[6:7], off offset:192
	global_load_dwordx4 v[112:115], v[6:7], off offset:224
	v_lshl_add_u64 v[4:5], v[4:5], 0, v[8:9]
	v_lshlrev_b32_e32 v2, 2, v2
	ds_bpermute_b32 v2, v2, v192
	s_xor_b64 s[2:3], s[94:95], -1
	s_mov_b32 s0, 1
	s_mov_b64 s[94:95], 0
	s_and_b64 vcc, exec, s[2:3]
	v_lshl_add_u64 v[4:5], v[4:5], 0, v[124:125]
	s_waitcnt lgkmcnt(0)
	v_add_f32_e32 v2, v192, v2
	v_rcp_f32_e32 v2, v2
	s_nop 0
	s_waitcnt vmcnt(7)
	v_permlane32_swap_b32_e32 v84, v86
	v_permlane32_swap_b32_e32 v85, v87
	v_lshlrev_b32_e32 v116, 16, v84
	v_and_b32_e32 v117, 0xffff0000, v84
	v_lshlrev_b32_e32 v118, 16, v85
	v_and_b32_e32 v119, 0xffff0000, v85
	v_pk_mul_f32 v[66:67], v[66:67], v[2:3] op_sel_hi:[1,0]
	v_pk_mul_f32 v[68:69], v[68:69], v[2:3] op_sel_hi:[1,0]
	v_pk_mul_f32 v[66:67], v[66:67], v[116:117]
	v_pk_mul_f32 v[68:69], v[68:69], v[118:119]
	v_lshlrev_b32_e32 v120, 16, v86
	v_and_b32_e32 v121, 0xffff0000, v86
	v_lshlrev_b32_e32 v122, 16, v87
	v_and_b32_e32 v123, 0xffff0000, v87
	v_pk_mul_f32 v[70:71], v[70:71], v[2:3] op_sel_hi:[1,0]
	v_pk_mul_f32 v[72:73], v[72:73], v[2:3] op_sel_hi:[1,0]
	v_pk_mul_f32 v[70:71], v[70:71], v[120:121]
	v_pk_mul_f32 v[72:73], v[72:73], v[122:123]
	v_cvt_pk_bf16_f32 v66, v66, v67
	v_cvt_pk_bf16_f32 v67, v68, v69
	v_cvt_pk_bf16_f32 v68, v70, v71
	v_cvt_pk_bf16_f32 v69, v72, v73
	s_nop 1
	v_permlane32_swap_b32_e32 v66, v68
	v_permlane32_swap_b32_e32 v67, v69
	global_store_dwordx4 v[4:5], v[66:69], off
	s_waitcnt vmcnt(7)
	v_permlane32_swap_b32_e32 v88, v90
	v_permlane32_swap_b32_e32 v89, v91
	v_lshlrev_b32_e32 v116, 16, v88
	v_and_b32_e32 v117, 0xffff0000, v88
	v_lshlrev_b32_e32 v118, 16, v89
	v_and_b32_e32 v119, 0xffff0000, v89
	v_pk_mul_f32 v[74:75], v[74:75], v[2:3] op_sel_hi:[1,0]
	v_pk_mul_f32 v[76:77], v[76:77], v[2:3] op_sel_hi:[1,0]
	v_pk_mul_f32 v[74:75], v[74:75], v[116:117]
	v_pk_mul_f32 v[76:77], v[76:77], v[118:119]
	v_lshlrev_b32_e32 v120, 16, v90
	v_and_b32_e32 v121, 0xffff0000, v90
	v_lshlrev_b32_e32 v122, 16, v91
	v_and_b32_e32 v123, 0xffff0000, v91
	v_pk_mul_f32 v[78:79], v[78:79], v[2:3] op_sel_hi:[1,0]
	v_pk_mul_f32 v[80:81], v[80:81], v[2:3] op_sel_hi:[1,0]
	v_pk_mul_f32 v[78:79], v[78:79], v[120:121]
	v_pk_mul_f32 v[80:81], v[80:81], v[122:123]
	v_cvt_pk_bf16_f32 v74, v74, v75
	v_cvt_pk_bf16_f32 v75, v76, v77
	v_cvt_pk_bf16_f32 v76, v78, v79
	v_cvt_pk_bf16_f32 v77, v80, v81
	s_nop 1
	v_permlane32_swap_b32_e32 v74, v76
	v_permlane32_swap_b32_e32 v75, v77
	global_store_dwordx4 v[4:5], v[74:77], off offset:32
	s_waitcnt vmcnt(7)
	v_permlane32_swap_b32_e32 v92, v94
	v_permlane32_swap_b32_e32 v93, v95
	v_lshlrev_b32_e32 v116, 16, v92
	v_and_b32_e32 v117, 0xffff0000, v92
	v_lshlrev_b32_e32 v118, 16, v93
	v_and_b32_e32 v119, 0xffff0000, v93
	v_pk_mul_f32 v[50:51], v[50:51], v[2:3] op_sel_hi:[1,0]
	v_pk_mul_f32 v[52:53], v[52:53], v[2:3] op_sel_hi:[1,0]
	v_pk_mul_f32 v[50:51], v[50:51], v[116:117]
	v_pk_mul_f32 v[52:53], v[52:53], v[118:119]
	v_lshlrev_b32_e32 v120, 16, v94
	v_and_b32_e32 v121, 0xffff0000, v94
	v_lshlrev_b32_e32 v122, 16, v95
	v_and_b32_e32 v123, 0xffff0000, v95
	v_pk_mul_f32 v[54:55], v[54:55], v[2:3] op_sel_hi:[1,0]
	v_pk_mul_f32 v[56:57], v[56:57], v[2:3] op_sel_hi:[1,0]
	v_pk_mul_f32 v[54:55], v[54:55], v[120:121]
	v_pk_mul_f32 v[56:57], v[56:57], v[122:123]
	v_cvt_pk_bf16_f32 v50, v50, v51
	v_cvt_pk_bf16_f32 v51, v52, v53
	v_cvt_pk_bf16_f32 v52, v54, v55
	v_cvt_pk_bf16_f32 v53, v56, v57
	s_nop 1
	v_permlane32_swap_b32_e32 v50, v52
	v_permlane32_swap_b32_e32 v51, v53
	global_store_dwordx4 v[4:5], v[50:53], off offset:64
	s_waitcnt vmcnt(7)
; #define GAS __attribute__((address_space(1)))
; __device__ __forceinline__ unsigned cvtpk(float lo, float hi) { typedef __bf16 b2 __attribute__((ext_vector_type(2))); f32x2 v = {lo, hi}; b2 b = __builtin_convertvector(v, b2); return __builtin_bit_cast(unsigned, b); }
;     ...
;         const bf16* GB = (const bf16*)(F.ws + WS_GB) + (size_t)qrow * D + hcol; bf16* orow = OB + (size_t)qrow * D + hcol;
; #pragma unroll
;         for (int d = 0; d < 4; ++d)
; #pragma unroll
;             for (int rg = 0; rg < 4; ++rg) { const int dc = d * 32 + 8 * rg + 4 * hi; const v2u gg = *(const GAS v2u*)(GB + dc);
;                 const float y0 = o[d][4 * rg + 0] * inv * bf_lo(gg.x), y1 = o[d][4 * rg + 1] * inv * bf_hi(gg.x), y2 = o[d][4 * rg + 2] * inv * bf_lo(gg.y), y3 = o[d][4 * rg + 3] * inv * bf_hi(gg.y);
;                 v2u wv; wv.x = cvtpk(y0, y1); wv.y = cvtpk(y2, y3); *(GAS v2u*)(orow + dc) = wv; }
	v_permlane32_swap_b32_e32 v96, v98
	v_permlane32_swap_b32_e32 v97, v99
	v_lshlrev_b32_e32 v116, 16, v96
	v_and_b32_e32 v117, 0xffff0000, v96
	v_lshlrev_b32_e32 v118, 16, v97
	v_and_b32_e32 v119, 0xffff0000, v97
	v_pk_mul_f32 v[58:59], v[58:59], v[2:3] op_sel_hi:[1,0]
	v_pk_mul_f32 v[60:61], v[60:61], v[2:3] op_sel_hi:[1,0]
	v_pk_mul_f32 v[58:59], v[58:59], v[116:117]
	v_pk_mul_f32 v[60:61], v[60:61], v[118:119]
	v_lshlrev_b32_e32 v120, 16, v98
	v_and_b32_e32 v121, 0xffff0000, v98
	v_lshlrev_b32_e32 v122, 16, v99
	v_and_b32_e32 v123, 0xffff0000, v99
	v_pk_mul_f32 v[62:63], v[62:63], v[2:3] op_sel_hi:[1,0]
	v_pk_mul_f32 v[64:65], v[64:65], v[2:3] op_sel_hi:[1,0]
	v_pk_mul_f32 v[62:63], v[62:63], v[120:121]
	v_pk_mul_f32 v[64:65], v[64:65], v[122:123]
	v_cvt_pk_bf16_f32 v58, v58, v59
	v_cvt_pk_bf16_f32 v59, v60, v61
	v_cvt_pk_bf16_f32 v60, v62, v63
	v_cvt_pk_bf16_f32 v61, v64, v65
	s_nop 1
	v_permlane32_swap_b32_e32 v58, v60
	v_permlane32_swap_b32_e32 v59, v61
	global_store_dwordx4 v[4:5], v[58:61], off offset:96
	s_waitcnt vmcnt(7)
	v_permlane32_swap_b32_e32 v100, v102
	v_permlane32_swap_b32_e32 v101, v103
	v_lshlrev_b32_e32 v116, 16, v100
	v_and_b32_e32 v117, 0xffff0000, v100
	v_lshlrev_b32_e32 v118, 16, v101
	v_and_b32_e32 v119, 0xffff0000, v101
	v_pk_mul_f32 v[34:35], v[34:35], v[2:3] op_sel_hi:[1,0]
	v_pk_mul_f32 v[36:37], v[36:37], v[2:3] op_sel_hi:[1,0]
	v_pk_mul_f32 v[34:35], v[34:35], v[116:117]
	v_pk_mul_f32 v[36:37], v[36:37], v[118:119]
	v_lshlrev_b32_e32 v120, 16, v102
	v_and_b32_e32 v121, 0xffff0000, v102
	v_lshlrev_b32_e32 v122, 16, v103
	v_and_b32_e32 v123, 0xffff0000, v103
	v_pk_mul_f32 v[38:39], v[38:39], v[2:3] op_sel_hi:[1,0]
	v_pk_mul_f32 v[40:41], v[40:41], v[2:3] op_sel_hi:[1,0]
	v_pk_mul_f32 v[38:39], v[38:39], v[120:121]
	v_pk_mul_f32 v[40:41], v[40:41], v[122:123]
	v_cvt_pk_bf16_f32 v34, v34, v35
	v_cvt_pk_bf16_f32 v35, v36, v37
	v_cvt_pk_bf16_f32 v36, v38, v39
	v_cvt_pk_bf16_f32 v37, v40, v41
	s_nop 1
	v_permlane32_swap_b32_e32 v34, v36
	v_permlane32_swap_b32_e32 v35, v37
	global_store_dwordx4 v[4:5], v[34:37], off offset:128
	s_waitcnt vmcnt(7)
	v_permlane32_swap_b32_e32 v104, v106
	v_permlane32_swap_b32_e32 v105, v107
	v_lshlrev_b32_e32 v116, 16, v104
	v_and_b32_e32 v117, 0xffff0000, v104
	v_lshlrev_b32_e32 v118, 16, v105
	v_and_b32_e32 v119, 0xffff0000, v105
	v_pk_mul_f32 v[42:43], v[42:43], v[2:3] op_sel_hi:[1,0]
	v_pk_mul_f32 v[44:45], v[44:45], v[2:3] op_sel_hi:[1,0]
	v_pk_mul_f32 v[42:43], v[42:43], v[116:117]
	v_pk_mul_f32 v[44:45], v[44:45], v[118:119]
	v_lshlrev_b32_e32 v120, 16, v106
	v_and_b32_e32 v121, 0xffff0000, v106
	v_lshlrev_b32_e32 v122, 16, v107
	v_and_b32_e32 v123, 0xffff0000, v107
	v_pk_mul_f32 v[46:47], v[46:47], v[2:3] op_sel_hi:[1,0]
	v_pk_mul_f32 v[48:49], v[48:49], v[2:3] op_sel_hi:[1,0]
	v_pk_mul_f32 v[46:47], v[46:47], v[120:121]
	v_pk_mul_f32 v[48:49], v[48:49], v[122:123]
	v_cvt_pk_bf16_f32 v42, v42, v43
	v_cvt_pk_bf16_f32 v43, v44, v45
	v_cvt_pk_bf16_f32 v44, v46, v47
	v_cvt_pk_bf16_f32 v45, v48, v49
	s_nop 1
	v_permlane32_swap_b32_e32 v42, v44
	v_permlane32_swap_b32_e32 v43, v45
	global_store_dwordx4 v[4:5], v[42:45], off offset:160
	s_waitcnt vmcnt(7)
	v_permlane32_swap_b32_e32 v108, v110
	v_permlane32_swap_b32_e32 v109, v111
	v_lshlrev_b32_e32 v116, 16, v108
	v_and_b32_e32 v117, 0xffff0000, v108
	v_lshlrev_b32_e32 v118, 16, v109
	v_and_b32_e32 v119, 0xffff0000, v109
	v_pk_mul_f32 v[18:19], v[18:19], v[2:3] op_sel_hi:[1,0]
	v_pk_mul_f32 v[20:21], v[20:21], v[2:3] op_sel_hi:[1,0]
	v_pk_mul_f32 v[18:19], v[18:19], v[116:117]
	v_pk_mul_f32 v[20:21], v[20:21], v[118:119]
	v_lshlrev_b32_e32 v120, 16, v110
	v_and_b32_e32 v121, 0xffff0000, v110
	v_lshlrev_b32_e32 v122, 16, v111
	v_and_b32_e32 v123, 0xffff0000, v111
	v_pk_mul_f32 v[22:23], v[22:23], v[2:3] op_sel_hi:[1,0]
	v_pk_mul_f32 v[24:25], v[24:25], v[2:3] op_sel_hi:[1,0]
	v_pk_mul_f32 v[22:23], v[22:23], v[120:121]
	v_pk_mul_f32 v[24:25], v[24:25], v[122:123]
	v_cvt_pk_bf16_f32 v18, v18, v19
	v_cvt_pk_bf16_f32 v19, v20, v21
	v_cvt_pk_bf16_f32 v20, v22, v23
	v_cvt_pk_bf16_f32 v21, v24, v25
	s_nop 1
	v_permlane32_swap_b32_e32 v18, v20
	v_permlane32_swap_b32_e32 v19, v21
	global_store_dwordx4 v[4:5], v[18:21], off offset:192
	s_waitcnt vmcnt(7)
	v_permlane32_swap_b32_e32 v112, v114
	v_permlane32_swap_b32_e32 v113, v115
	v_lshlrev_b32_e32 v116, 16, v112
	v_and_b32_e32 v117, 0xffff0000, v112
	v_lshlrev_b32_e32 v118, 16, v113
	v_and_b32_e32 v119, 0xffff0000, v113
	v_pk_mul_f32 v[26:27], v[26:27], v[2:3] op_sel_hi:[1,0]
	v_pk_mul_f32 v[28:29], v[28:29], v[2:3] op_sel_hi:[1,0]
	v_pk_mul_f32 v[26:27], v[26:27], v[116:117]
	v_pk_mul_f32 v[28:29], v[28:29], v[118:119]
	v_lshlrev_b32_e32 v120, 16, v114
	v_and_b32_e32 v121, 0xffff0000, v114
	v_lshlrev_b32_e32 v122, 16, v115
	v_and_b32_e32 v123, 0xffff0000, v115
	v_pk_mul_f32 v[30:31], v[30:31], v[2:3] op_sel_hi:[1,0]
	v_pk_mul_f32 v[32:33], v[32:33], v[2:3] op_sel_hi:[1,0]
	v_pk_mul_f32 v[30:31], v[30:31], v[120:121]
	v_pk_mul_f32 v[32:33], v[32:33], v[122:123]
	v_cvt_pk_bf16_f32 v26, v26, v27
	v_cvt_pk_bf16_f32 v27, v28, v29
	v_cvt_pk_bf16_f32 v28, v30, v31
	v_cvt_pk_bf16_f32 v29, v32, v33
	s_nop 1
	v_permlane32_swap_b32_e32 v26, v28
	v_permlane32_swap_b32_e32 v27, v29
	global_store_dwordx4 v[4:5], v[26:29], off offset:224
	s_cbranch_vccnz .LBB0_2121
